# MLA attention loop: coalesced 7 paired lgkmcnt waits before independent MFMA pairs (on top of v48)
# baseline (speedup 1.0000x reference)
; #define PIN() do { asm volatile("" ::: "memory"); __builtin_amdgcn_sched_barrier(0); } while (0)
; #define GLOAD(kt_) do { const bf16_t* kp_ = Kb + (size_t)(kt_) * 64 * DQK; const bf16_t* vp_ = VTb + (kt_) * 64; \
;     kreg0 = *(const uint4*)(kp_ + kgo[0]); kreg1 = *(const uint4*)(kp_ + kgo[1]); if (NKC > 2) kreg2 = *(const uint4*)(kp_ + kgo[2]); \
;     vreg0 = *(const uint4*)(vp_ + vgo0); vreg1 = *(const uint4*)(vp_ + vgo1); } while (0)
; #define KLD(dst_, s_) do { dst_[0] = *(const bf16x8*)(kbase + (s_) * 32); dst_[1] = *(const bf16x8*)(kbase + 32 * KSTR + (s_) * 32); \
;         dst_[2] = *(const bf16x8*)(kbase + ((s_) + 1) * 32); dst_[3] = *(const bf16x8*)(kbase + 32 * KSTR + ((s_) + 1) * 32); } while (0)
; template <int DQK, int NM>
; DI void attn_item(const bf16_t* Qb, const bf16_t* Kb, size_t mstride, const bf16_t* VTb,
;                   int q0, int nkt, float cs, bf16_t* Orow  , float lam, float outscale, const float* subw, char* smem) {
;     ...
;   for (int kt = 0; kt < nkt; ++kt) {
;     const char* cur = smem + (kt & 1) * BUF;
;     GLOAD(kt + 1 < nkt ? kt + 1 : kt);
;     PIN();
;     f32x16 sacc[2];
; #pragma unroll
;     for (int kb = 0; kb < 2; ++kb)
; #pragma unroll
;       for (int i = 0; i < 16; ++i) sacc[kb][i] = 0.f;
;     const char* kbase = cur + (m * 64 + l31) * KSTR + hh * 16;
;     {
;       bf16x8 kfa[4], kfb[4];
;     ...
;       KLD(kfa, 0);
; #pragma unroll
;       for (int g = 0; g < NS / 2; ++g) {
;         PIN();
;         if (g + 1 < NS / 2) { if (g & 1) KLD(kfa, 2 * g + 2); else KLD(kfb, 2 * g + 2); }
;         PIN();
;         if (g & 1) KMM(kfb, 2 * g); else KMM(kfa, 2 * g);
;       }
;     ...
;     }
;     float mx = sacc[0][0];
; #pragma unroll
;     for (int i = 1; i < 16; ++i) mx = fmaxf(mx, sacc[0][i]);
; #pragma unroll
;     for (int i = 0; i < 16; ++i) mx = fmaxf(mx, sacc[1][i]);
;     {
;       const auto rr = __builtin_amdgcn_permlane32_swap(__float_as_uint(mx), __float_as_uint(mx), false, false);
;       mx = fmaxf(__uint_as_float(rr[0]), __uint_as_float(rr[1]));
;     }
;     if (__any((mx - mrun) * cs > 8.f)) {
;       const float mnew = fmaxf(mrun, mx);
;       const float alpha = __builtin_amdgcn_exp2f((mrun - mnew) * cs);
;       mrun = mnew;
;       lrun *= alpha;
; #pragma unroll
;       for (int db = 0; db < 4; ++db)
; #pragma unroll
;         for (int i = 0; i < 16; ++i) oacc[db][i] *= alpha;
;     }
.LBB0_127:
	global_load_dwordx4 v[158:161], v[190:191], off
	global_load_dwordx4 v[154:157], v[192:193], off
	global_load_dwordx4 v[162:165], v[194:195], off
	global_load_dwordx4 v[150:153], v[186:187], off
	global_load_dwordx4 v[146:149], v[188:189], off
	s_and_b32 s24, 1, s37
	s_cselect_b32 s25, 0, 0xac00
	s_add_i32 s25, s25, 0
	v_add3_u32 v196, s25, v217, v170
	ds_read_b128 v[64:67], v196
	ds_read_b128 v[220:223], v196 offset:32
	ds_read_b128 v[68:71], v196 offset:12800
	ds_read_b128 v[224:227], v196 offset:12832
	ds_read_b128 v[228:231], v196 offset:64
	ds_read_b128 v[232:235], v196 offset:96
	ds_read_b128 v[236:239], v196 offset:12864
	ds_read_b128 v[240:243], v196 offset:12896
	s_waitcnt lgkmcnt(5)
	v_mfma_f32_32x32x16_bf16 v[80:95], v[64:67], v[142:145], 0
	v_mfma_f32_32x32x16_bf16 v[64:79], v[68:71], v[142:145], 0
	v_mfma_f32_32x32x16_bf16 v[80:95], v[220:223], v[136:139], v[80:95]
	s_waitcnt lgkmcnt(4)
	v_mfma_f32_32x32x16_bf16 v[64:79], v[224:227], v[136:139], v[64:79]
	ds_read_b128 v[220:223], v196 offset:128
	ds_read_b128 v[224:227], v196 offset:160
	ds_read_b128 v[244:247], v196 offset:12928
	ds_read_b128 v[248:251], v196 offset:12960
	s_waitcnt lgkmcnt(5)
	v_mfma_f32_32x32x16_bf16 v[80:95], v[228:231], v[132:135], v[80:95]
	v_mfma_f32_32x32x16_bf16 v[64:79], v[236:239], v[132:135], v[64:79]
	v_mfma_f32_32x32x16_bf16 v[80:95], v[232:235], v[128:131], v[80:95]
	s_waitcnt lgkmcnt(4)
	v_mfma_f32_32x32x16_bf16 v[64:79], v[240:243], v[128:131], v[64:79]
	ds_read_b128 v[228:231], v196 offset:192
	ds_read_b128 v[232:235], v196 offset:224
	ds_read_b128 v[236:239], v196 offset:12992
	ds_read_b128 v[240:243], v196 offset:13024
	s_waitcnt lgkmcnt(5)
	v_mfma_f32_32x32x16_bf16 v[80:95], v[220:223], v[124:127], v[80:95]
	v_mfma_f32_32x32x16_bf16 v[64:79], v[244:247], v[124:127], v[64:79]
	v_mfma_f32_32x32x16_bf16 v[80:95], v[224:227], v[120:123], v[80:95]
	s_waitcnt lgkmcnt(4)
	v_mfma_f32_32x32x16_bf16 v[64:79], v[248:251], v[120:123], v[64:79]
	ds_read_b128 v[220:223], v196 offset:256
	ds_read_b128 v[224:227], v196 offset:288
	ds_read_b128 v[244:247], v196 offset:13056
	ds_read_b128 v[248:251], v196 offset:13088
	s_waitcnt lgkmcnt(5)
	v_mfma_f32_32x32x16_bf16 v[80:95], v[228:231], v[116:119], v[80:95]
	v_mfma_f32_32x32x16_bf16 v[64:79], v[236:239], v[116:119], v[64:79]
	v_mfma_f32_32x32x16_bf16 v[80:95], v[232:235], v[112:115], v[80:95]
	s_waitcnt lgkmcnt(4)
	v_mfma_f32_32x32x16_bf16 v[64:79], v[240:243], v[112:115], v[64:79]
	ds_read_b128 v[228:231], v196 offset:320
	ds_read_b128 v[232:235], v196 offset:352
	ds_read_b128 v[236:239], v196 offset:13120
	ds_read_b128 v[240:243], v196 offset:13152
	s_waitcnt lgkmcnt(5)
	v_mfma_f32_32x32x16_bf16 v[80:95], v[220:223], v[108:111], v[80:95]
	v_mfma_f32_32x32x16_bf16 v[64:79], v[244:247], v[108:111], v[64:79]
	v_mfma_f32_32x32x16_bf16 v[80:95], v[224:227], v[104:107], v[80:95]
	s_waitcnt lgkmcnt(3)
	v_mfma_f32_32x32x16_bf16 v[64:79], v[248:251], v[104:107], v[64:79]
	v_mfma_f32_32x32x16_bf16 v[80:95], v[228:231], v[100:103], v[80:95]
	s_waitcnt lgkmcnt(1)
	v_mfma_f32_32x32x16_bf16 v[80:95], v[232:235], v[96:99], v[80:95]
	v_mfma_f32_32x32x16_bf16 v[64:79], v[236:239], v[100:103], v[64:79]
	s_mov_b64 s[34:35], 0x80
	s_add_i32 s37, s37, 1
	v_lshl_add_u64 v[186:187], v[186:187], 0, s[34:35]
	v_lshl_add_u64 v[188:189], v[188:189], 0, s[34:35]
	s_mov_b64 s[34:35], 0x6000
	v_lshl_add_u64 v[190:191], v[190:191], 0, s[34:35]
	v_lshl_add_u64 v[192:193], v[192:193], 0, s[34:35]
	v_lshl_add_u64 v[194:195], v[194:195], 0, s[34:35]
	s_nop 1
	v_max_f32_e32 v196, v80, v81
	v_max3_f32 v196, v196, v82, v83
	v_max3_f32 v196, v196, v84, v85
	v_max3_f32 v196, v196, v86, v87
	v_max3_f32 v196, v196, v88, v89
	s_waitcnt lgkmcnt(0)
	v_mfma_f32_32x32x16_bf16 v[64:79], v[240:243], v[96:99], v[64:79]
	v_max3_f32 v196, v196, v90, v91
	v_max3_f32 v196, v196, v92, v93
	v_max3_f32 v196, v196, v94, v95
	s_cmp_eq_u32 s24, 1
	s_cselect_b32 s24, 0xac00, 0
	v_add_u32_e32 v206, s24, v197
	v_add_u32_e32 v211, s24, v216
	s_nop 4
	v_max3_f32 v196, v196, v64, v65
	v_max3_f32 v196, v196, v66, v67
	v_max3_f32 v196, v196, v68, v69
	v_max3_f32 v196, v196, v70, v71
	v_max3_f32 v196, v196, v72, v73
	v_max3_f32 v196, v196, v74, v75
	v_max3_f32 v196, v196, v76, v77
	v_max3_f32 v196, v196, v78, v79
	v_mov_b32_e32 v219, v196
	s_nop 1
	v_permlane32_swap_b32_e32 v196, v219
	v_max_f32_e32 v196, v196, v219
	v_sub_f32_e32 v219, v196, v218
	v_mul_f32_e32 v219, 0x3dd53b95, v219
	v_cmp_lt_f32_e32 vcc, s5, v219
	s_cbranch_vccz .LBB0_126
	v_max_f32_e32 v196, v196, v196
	v_max_f32_e32 v219, v218, v218
	v_max_f32_e32 v219, v219, v196
	v_sub_f32_e32 v196, v218, v219
	v_mul_f32_e32 v196, 0x3dd53b95, v196
	v_exp_f32_e32 v196, v196
	v_mov_b32_e32 v218, v219
	v_pk_mul_f32 v[46:47], v[46:47], v[196:197] op_sel_hi:[1,0]
	v_pk_mul_f32 v[44:45], v[44:45], v[196:197] op_sel_hi:[1,0]
	v_pk_mul_f32 v[42:43], v[42:43], v[196:197] op_sel_hi:[1,0]
	v_pk_mul_f32 v[40:41], v[40:41], v[196:197] op_sel_hi:[1,0]
	v_pk_mul_f32 v[38:39], v[38:39], v[196:197] op_sel_hi:[1,0]
	v_pk_mul_f32 v[36:37], v[36:37], v[196:197] op_sel_hi:[1,0]
	v_pk_mul_f32 v[34:35], v[34:35], v[196:197] op_sel_hi:[1,0]
	v_pk_mul_f32 v[32:33], v[32:33], v[196:197] op_sel_hi:[1,0]
	v_pk_mul_f32 v[62:63], v[62:63], v[196:197] op_sel_hi:[1,0]
	v_pk_mul_f32 v[60:61], v[60:61], v[196:197] op_sel_hi:[1,0]
	v_pk_mul_f32 v[58:59], v[58:59], v[196:197] op_sel_hi:[1,0]
	v_pk_mul_f32 v[56:57], v[56:57], v[196:197] op_sel_hi:[1,0]
	v_pk_mul_f32 v[54:55], v[54:55], v[196:197] op_sel_hi:[1,0]
	v_pk_mul_f32 v[52:53], v[52:53], v[196:197] op_sel_hi:[1,0]
	v_pk_mul_f32 v[50:51], v[50:51], v[196:197] op_sel_hi:[1,0]
	v_pk_mul_f32 v[48:49], v[48:49], v[196:197] op_sel_hi:[1,0]
	v_pk_mul_f32 v[30:31], v[30:31], v[196:197] op_sel_hi:[1,0]
	v_pk_mul_f32 v[28:29], v[28:29], v[196:197] op_sel_hi:[1,0]
	v_pk_mul_f32 v[26:27], v[26:27], v[196:197] op_sel_hi:[1,0]
	v_pk_mul_f32 v[24:25], v[24:25], v[196:197] op_sel_hi:[1,0]
	v_pk_mul_f32 v[22:23], v[22:23], v[196:197] op_sel_hi:[1,0]
	v_pk_mul_f32 v[20:21], v[20:21], v[196:197] op_sel_hi:[1,0]
	v_pk_mul_f32 v[18:19], v[18:19], v[196:197] op_sel_hi:[1,0]
	v_pk_mul_f32 v[16:17], v[16:17], v[196:197] op_sel_hi:[1,0]
	v_pk_mul_f32 v[14:15], v[14:15], v[196:197] op_sel_hi:[1,0]
	v_pk_mul_f32 v[12:13], v[12:13], v[196:197] op_sel_hi:[1,0]
	v_pk_mul_f32 v[10:11], v[10:11], v[196:197] op_sel_hi:[1,0]
	v_pk_mul_f32 v[8:9], v[8:9], v[196:197] op_sel_hi:[1,0]
	v_pk_mul_f32 v[6:7], v[6:7], v[196:197] op_sel_hi:[1,0]
	v_pk_mul_f32 v[4:5], v[4:5], v[196:197] op_sel_hi:[1,0]
	v_pk_mul_f32 v[2:3], v[2:3], v[196:197] op_sel_hi:[1,0]
	v_pk_mul_f32 v[0:1], v[0:1], v[196:197] op_sel_hi:[1,0]
	v_mul_f32_e32 v185, v185, v196
	s_branch .LBB0_126
